# attention tile loop: one static s_setprio 1 for waves 4..7 (the later-dispatched half) in front of the loop, reset to 0 behind it
# speedup vs baseline: 1.0124x; 1.0124x over previous
.LBB0_422:
	s_lshl_b32 s0, s39, 10
	s_and_b32 s6, s0, 0x800000
	s_lshl_b32 s0, s43, 1
	s_and_b32 s66, s0, 0x300
	s_lshl_b32 s0, s64, 11
	s_lshl_b32 s1, s64, 4
	s_and_b32 s0, s0, 0x2000
	s_and_b32 s1, s1, 0xffffff80
	s_add_i32 s1, s0, s1
	v_or_b32_e32 v171, s1, v170
	v_or_b32_e32 v0, v171, v169
	v_ashrrev_i32_e32 v1, 31, v0
	s_lshl_b32 s1, s64, 7
	v_lshlrev_b64 v[0:1], 10, v[0:1]
	s_and_b32 s65, s1, 0x180
	v_lshl_add_u64 v[0:1], s[86:87], 0, v[0:1]
	s_lshl_b32 s4, s65, 1
	s_mov_b32 s5, s7
	v_lshl_add_u64 v[0:1], v[0:1], 0, s[4:5]
	s_lshl_b32 s5, s0, 10
	s_add_u32 s0, s33, s5
	s_addc_u32 s1, s34, 0
	s_add_u32 s0, s0, s4
	v_mov_b32_e32 v174, v168
	v_lshl_add_u64 v[0:1], v[160:161], 1, v[0:1]
	s_addc_u32 s1, s1, 0
	v_lshl_add_u64 v[0:1], v[0:1], 0, v[162:163]
	v_ashrrev_i32_e32 v16, 4, v174
	s_add_u32 s5, s35, s5
	v_lshlrev_b32_e32 v20, 3, v174
	v_add_u32_e32 v18, 32, v16
	s_addc_u32 s16, s38, 0
	global_load_dwordx4 v[124:127], v[0:1], off
	global_load_dwordx4 v[120:123], v[0:1], off offset:32
	global_load_dwordx4 v[116:119], v[0:1], off offset:64
	global_load_dwordx4 v[112:115], v[0:1], off offset:96
	v_and_b32_e32 v0, 0x78, v20
	v_ashrrev_i32_e32 v17, 31, v16
	v_ashrrev_i32_e32 v19, 31, v18
	s_add_u32 s4, s5, s4
	v_lshlrev_b32_e32 v21, 1, v0
	v_lshlrev_b64 v[48:49], 10, v[16:17]
	v_lshlrev_b64 v[12:13], 10, v[18:19]
	s_addc_u32 s5, s16, 0
	v_or_b32_e32 v50, v48, v21
	v_mov_b32_e32 v51, v49
	v_or_b32_e32 v12, v12, v21
	v_lshl_add_u64 v[0:1], s[4:5], 0, v[50:51]
	v_lshl_add_u64 v[4:5], s[4:5], 0, v[12:13]
	s_barrier
	global_load_dwordx4 v[0:3], v[0:1], off
	s_nop 0
	global_load_dwordx4 v[4:7], v[4:5], off
	v_lshl_add_u64 v[8:9], s[0:1], 0, v[50:51]
	global_load_dwordx4 v[8:11], v[8:9], off
	v_lshl_add_u64 v[12:13], s[0:1], 0, v[12:13]
	global_load_dwordx4 v[12:15], v[12:13], off
	v_and_b32_e32 v22, 0xfffff0, v16
	v_lshlrev_b32_e32 v23, 1, v16
	v_lshrrev_b32_e32 v24, 1, v16
	v_and_b32_e32 v25, 3, v16
	v_and_or_b32 v22, v23, 8, v22
	v_and_or_b32 v23, v24, 4, v25
	v_and_b32_e32 v24, 0xfffff0, v18
	v_lshlrev_b32_e32 v25, 1, v18
	v_and_b32_e32 v17, 0x70, v174
	v_bfe_u32 v20, v20, 5, 2
	v_lshlrev_b32_e32 v16, 8, v16
	v_lshrrev_b32_e32 v22, 1, v22
	v_and_or_b32 v24, v25, 8, v24
	v_bitop3_b32 v183, v21, v16, v17 bitop3:0xde
	v_or_b32_e32 v16, v22, v20
	v_lshrrev_b32_e32 v22, 1, v24
	v_lshlrev_b32_e32 v23, 6, v23
	v_and_b32_e32 v26, 48, v21
	v_lshlrev_b32_e32 v16, 9, v16
	v_or_b32_e32 v20, v22, v20
	v_or3_b32 v184, v16, v23, v26
	v_lshlrev_b32_e32 v16, 9, v20
	v_bfe_u32 v172, v174, 5, 1
	v_ashrrev_i32_e32 v175, 8, v174
	v_lshlrev_b32_e32 v52, 4, v174
	v_or3_b32 v186, v16, v23, v26
	v_add_u32_e32 v84, 16, v184
	v_and_b32_e32 v173, 31, v174
	v_lshlrev_b32_e32 v19, 7, v175
	v_add_u32_e32 v24, 16, v183
	v_add_u32_e32 v85, 16, v186
	s_waitcnt vmcnt(0)
	v_lshlrev_b32_e32 v176, 4, v172
	v_lshlrev_b32_e32 v190, 8, v173
	v_and_b32_e32 v86, 63, v174
	v_lshl_add_u64 v[60:61], v[50:51], 0, s[14:15]
	v_lshl_add_u64 v[64:65], v[50:51], 0, s[36:37]
	v_lshl_add_u64 v[56:57], s[4:5], 0, v[64:65]
	v_lshl_add_u64 v[64:65], s[0:1], 0, v[64:65]
	s_cmp_lg_u32 16, -1
	s_cselect_b32 s16, 16, 0
	s_mov_b32 s17, s7
	s_mov_b32 s18, s7
	s_mov_b32 s19, s7
	s_mov_b32 s20, s7
	s_waitcnt vmcnt(3)
	ds_write_b128 v84, v[0:3]
	s_waitcnt vmcnt(2)
	ds_write_b128 v85, v[4:7]
	s_waitcnt vmcnt(1)
	ds_write_b128 v24, v[8:11] offset:49152
	v_and_b32_e32 v8, 0x70, v52
	v_lshlrev_b32_e32 v0, 8, v18
	v_bitop3_b32 v182, v176, v8, v19 bitop3:0x36
	v_bitop3_b32 v188, v21, v0, v17 bitop3:0xde
	v_add_u32_e32 v185, v182, v190
	v_add_u32_e32 v0, 16, v188
	v_add_u32_e32 v4, 16, v185
	s_waitcnt vmcnt(0)
	ds_write_b128 v0, v[12:15] offset:49152
	s_waitcnt lgkmcnt(0)
	s_barrier
	ds_read_b128 v[0:3], v4 offset:49152
	ds_read_b128 v[4:7], v4 offset:57344
	v_or_b32_e32 v9, v176, v19
	v_bitop3_b32 v187, v9, v8, 32 bitop3:0x36
	v_add_u32_e32 v189, v187, v190
	s_waitcnt lgkmcnt(0)
	v_mfma_f32_32x32x16_bf16 v[16:31], v[4:7], v[124:127], 0
	v_add_u32_e32 v4, 16, v189
	v_bitop3_b32 v193, v9, v8, s3 bitop3:0x36
	v_bitop3_b32 v191, v9, v8, 64 bitop3:0x36
	v_add_u32_e32 v194, v193, v190
	v_add_u32_e32 v192, v191, v190
	v_add_u32_e32 v8, 16, v194
	v_and_b32_e32 v5, 0x3fffffc0, v174
	v_mfma_f32_32x32x16_bf16 v[32:47], v[0:3], v[124:127], 0
	ds_read_b128 v[0:3], v4 offset:49152
	v_and_b32_e32 v11, 0xc0, v52
	v_add_u32_e32 v13, 16, v192
	ds_read_b128 v[52:55], v8 offset:57344
	v_lshl_add_u32 v177, v5, 2, s50
	ds_read_b128 v[4:7], v4 offset:57344
	v_lshlrev_b32_e32 v10, 3, v86
	s_waitcnt lgkmcnt(2)
	v_mfma_f32_32x32x16_bf16 v[32:47], v[0:3], v[120:123], v[32:47]
	v_lshlrev_b32_e32 v0, 1, v174
	v_and_b32_e32 v12, 32, v0
	ds_read_b128 v[0:3], v13 offset:49152
	v_and_or_b32 v11, v10, 24, v11
	s_mov_b32 s21, s7
	s_mov_b32 s22, s7
	s_mov_b32 s23, s7
	s_waitcnt lgkmcnt(0)
	v_mfma_f32_32x32x16_bf16 v[32:47], v[0:3], v[116:119], v[32:47]
	ds_read_b128 v[0:3], v8 offset:49152
	s_mov_b32 s24, s7
	s_mov_b32 s25, s7
	s_mov_b32 s26, s7
	s_mov_b32 s27, s7
	s_mov_b32 s28, s7
	s_mov_b32 s29, s7
	v_mfma_f32_32x32x16_bf16 v[16:31], v[4:7], v[120:123], v[16:31]
	v_and_b32_e32 v4, 0x100, v10
	v_lshlrev_b32_e32 v4, 3, v4
	v_or3_b32 v178, v11, v12, v4
	ds_read_b128 v[4:7], v13 offset:57344
	v_add_u32_e32 v181, s16, v178
	s_mov_b32 s16, s7
	s_mov_b32 s30, s7
	s_mov_b32 s31, s7
	s_waitcnt lgkmcnt(0)
	v_mfma_f32_32x32x16_bf16 v[16:31], v[4:7], v[116:119], v[16:31]
	v_lshl_add_u32 v179, v173, 2, v177
	v_mov_b32_e32 v196, 1.0
	v_mov_b32_e32 v180, 0
	v_mfma_f32_32x32x16_bf16 v[32:47], v[0:3], v[112:115], v[32:47]
	v_mov_b64_e32 v[0:1], s[16:17]
	v_mov_b64_e32 v[14:15], s[30:31]
	v_mov_b64_e32 v[2:3], s[18:19]
	v_mov_b64_e32 v[4:5], s[20:21]
	v_mov_b64_e32 v[6:7], s[22:23]
	v_mov_b64_e32 v[8:9], s[24:25]
	v_mov_b64_e32 v[10:11], s[26:27]
	v_mfma_f32_32x32x16_bf16 v[16:31], v[52:55], v[112:115], v[16:31]
	s_nop 3
	v_max_f32_e32 v52, v33, v33
	v_max_f32_e32 v53, v32, v32
	v_max_f32_e32 v52, v53, v52
	v_max3_f32 v52, v52, v34, v35
	v_max3_f32 v52, v52, v36, v37
	v_max3_f32 v52, v52, v38, v39
	v_max3_f32 v52, v52, v40, v41
	v_max3_f32 v52, v52, v42, v43
	v_max3_f32 v52, v52, v44, v45
	v_max3_f32 v66, v52, v46, v47
	v_lshl_add_u64 v[52:53], s[4:5], 0, v[60:61]
	v_lshl_add_u64 v[60:61], s[0:1], 0, v[60:61]
	global_load_dwordx4 v[52:55], v[52:53], off
	s_nop 0
	global_load_dwordx4 v[56:59], v[56:57], off
	v_mov_b64_e32 v[12:13], s[28:29]
	global_load_dwordx4 v[60:63], v[60:61], off
	s_mov_b32 s19, 1
	global_load_dwordx4 v[80:83], v[64:65], off
	v_max3_f32 v64, v66, v16, v17
	v_max3_f32 v64, v64, v18, v19
	v_max3_f32 v64, v64, v20, v21
	v_max3_f32 v64, v64, v22, v23
	v_max3_f32 v64, v64, v24, v25
	v_max3_f32 v64, v64, v26, v27
	v_max3_f32 v64, v64, v28, v29
	v_max3_f32 v70, v64, v30, v31
	v_lshl_add_u64 v[64:65], v[50:51], 0, s[40:41]
	v_lshl_add_u64 v[66:67], s[0:1], 0, v[64:65]
	v_lshl_add_u64 v[50:51], v[50:51], 0, s[44:45]
	v_lshl_add_u64 v[64:65], s[4:5], 0, v[64:65]
	v_lshl_add_u64 v[68:69], s[0:1], 0, v[50:51]
	global_load_dwordx4 v[136:139], v[66:67], off
	global_load_dwordx4 v[128:131], v[68:69], off
	v_lshl_add_u64 v[50:51], s[4:5], 0, v[50:51]
	global_load_dwordx4 v[140:143], v[64:65], off
	global_load_dwordx4 v[132:135], v[50:51], off
	v_mov_b32_e32 v71, v70
	s_nop 1
	v_permlane32_swap_b32_e32 v70, v71
	v_max_f32_e32 v50, v71, v71
	v_max_f32_e32 v51, v70, v70
	v_max_f32_e32 v50, v51, v50
	v_sub_f32_e32 v64, v16, v50
	v_add_u32_e32 v16, s58, v183
	v_sub_f32_e32 v32, v32, v50
	v_sub_f32_e32 v33, v33, v50
	v_sub_f32_e32 v34, v34, v50
	v_sub_f32_e32 v35, v35, v50
	v_sub_f32_e32 v36, v36, v50
	v_sub_f32_e32 v37, v37, v50
	v_sub_f32_e32 v38, v38, v50
	v_sub_f32_e32 v39, v39, v50
	v_sub_f32_e32 v40, v40, v50
	v_sub_f32_e32 v41, v41, v50
	v_sub_f32_e32 v42, v42, v50
	v_sub_f32_e32 v43, v43, v50
	v_sub_f32_e32 v44, v44, v50
	v_sub_f32_e32 v45, v45, v50
	v_sub_f32_e32 v46, v46, v50
	v_sub_f32_e32 v47, v47, v50
	v_sub_f32_e32 v66, v18, v50
	s_waitcnt vmcnt(4)
	s_waitcnt vmcnt(7)
	ds_write_b128 v84, v[52:55] offset:16384
	s_waitcnt vmcnt(6)
	ds_write_b128 v85, v[56:59] offset:16384
	v_and_b32_e32 v18, 15, v174
	s_waitcnt vmcnt(5)
	ds_write_b128 v16, v[60:63]
	v_add_u32_e32 v16, s58, v188
	v_sub_f32_e32 v65, v17, v50
	v_exp_f32_e32 v152, v32
	v_exp_f32_e32 v153, v33
	v_exp_f32_e32 v154, v34
	v_exp_f32_e32 v155, v35
	v_exp_f32_e32 v156, v36
	v_exp_f32_e32 v157, v37
	v_exp_f32_e32 v158, v38
	v_exp_f32_e32 v159, v39
	v_exp_f32_e32 v144, v40
	v_exp_f32_e32 v145, v41
	v_exp_f32_e32 v146, v42
	v_exp_f32_e32 v147, v43
	v_exp_f32_e32 v148, v44
	v_exp_f32_e32 v149, v45
	v_exp_f32_e32 v150, v46
	v_exp_f32_e32 v151, v47
	s_waitcnt vmcnt(4)
	ds_write_b128 v16, v[80:83]
	v_lshl_add_u64 v[16:17], s[6:7], 0, v[48:49]
	v_lshlrev_b32_e32 v18, 4, v18
	v_or3_b32 v16, v16, s66, v18
	v_add_f32_e32 v195, 0, v50
	v_sub_f32_e32 v79, v31, v50
	v_sub_f32_e32 v78, v30, v50
	v_sub_f32_e32 v77, v29, v50
	v_sub_f32_e32 v76, v28, v50
	v_sub_f32_e32 v75, v27, v50
	v_sub_f32_e32 v74, v26, v50
	v_sub_f32_e32 v73, v25, v50
	v_sub_f32_e32 v72, v24, v50
	v_sub_f32_e32 v71, v23, v50
	v_sub_f32_e32 v70, v22, v50
	v_sub_f32_e32 v69, v21, v50
	v_sub_f32_e32 v68, v20, v50
	v_sub_f32_e32 v67, v19, v50
	v_lshl_add_u64 v[166:167], s[12:13], 0, v[16:17]
	v_mov_b64_e32 v[62:63], v[14:15]
	v_mov_b64_e32 v[46:47], v[14:15]
	v_mov_b64_e32 v[30:31], v[14:15]
	v_cmp_gt_u32_e64 s[0:1], 32, v86
	v_mov_b64_e32 v[60:61], v[12:13]
	v_mov_b64_e32 v[58:59], v[10:11]
	v_mov_b64_e32 v[56:57], v[8:9]
	v_mov_b64_e32 v[54:55], v[6:7]
	v_mov_b64_e32 v[52:53], v[4:5]
	v_mov_b64_e32 v[50:51], v[2:3]
	v_mov_b64_e32 v[48:49], v[0:1]
	v_mov_b64_e32 v[44:45], v[12:13]
	v_mov_b64_e32 v[42:43], v[10:11]
	v_mov_b64_e32 v[40:41], v[8:9]
	v_mov_b64_e32 v[38:39], v[6:7]
	v_mov_b64_e32 v[36:37], v[4:5]
	v_mov_b64_e32 v[34:35], v[2:3]
	v_mov_b64_e32 v[32:33], v[0:1]
	v_mov_b64_e32 v[28:29], v[12:13]
	v_mov_b64_e32 v[26:27], v[10:11]
	v_mov_b64_e32 v[24:25], v[8:9]
	v_mov_b64_e32 v[22:23], v[6:7]
	v_mov_b64_e32 v[20:21], v[4:5]
	v_mov_b64_e32 v[18:19], v[2:3]
	v_mov_b64_e32 v[16:17], v[0:1]
	s_mov_b32 s6, 1
	s_mov_b32 s18, 0
	s_waitcnt lgkmcnt(0)
	s_barrier
	v_add_co_u32_e32 v242, vcc, s61, v166
	s_nop 1
	v_addc_co_u32_e32 v243, vcc, -1, v167, vcc
	s_nop 0
	v_readfirstlane_b32 s98, v242
	v_readfirstlane_b32 s99, v243
	s_nop 1
	v_subrev_u32_e32 v242, s98, v242
	v_add_u32_e32 v243, 0x8000, v242
	v_add_u32_e32 v244, 0x1000000, v242
	v_add_u32_e32 v245, 0x1008000, v242
	v_cmp_lt_u32_e32 vcc, 0xff, v214
	s_nop 4
	s_cbranch_vccz .Lprio_a0
	s_setprio 1
.Lprio_a0:
.LBB0_423:
	s_lshl_b32 s16, s19, 14
	s_add_i32 s4, s16, 16
	v_add_u32_e32 v96, s4, v185
	ds_read_b128 v[198:201], v96 offset:49152
	ds_read_b128 v[202:205], v96 offset:57344
	v_xor_b32_e32 v80, 0x80000000, v195
	v_mov_b32_e32 v81, v80
	v_mov_b64_e32 v[82:83], v[80:81]
	v_mov_b64_e32 v[84:85], v[80:81]
	v_mov_b64_e32 v[86:87], v[80:81]
	v_mov_b64_e32 v[88:89], v[80:81]
	v_mov_b64_e32 v[90:91], v[80:81]
	v_mov_b64_e32 v[92:93], v[80:81]
	v_mov_b64_e32 v[94:95], v[80:81]
	v_exp_f32_e32 v221, v64
	s_waitcnt lgkmcnt(1)
	v_mfma_f32_32x32x16_bf16 v[96:111], v[198:201], v[124:127], v[80:95]
	v_add_f32_e32 v64, v153, v152
	v_add_f32_e32 v64, v154, v64
	v_add_u32_e32 v197, s4, v189
	v_add_f32_e32 v64, v155, v64
	v_add_f32_e32 v64, v156, v64
	v_add_f32_e32 v64, v157, v64
	v_add_f32_e32 v64, v158, v64
	s_waitcnt lgkmcnt(0)
	v_mfma_f32_32x32x16_bf16 v[80:95], v[202:205], v[124:127], v[80:95]
	ds_read_b128 v[198:201], v197 offset:49152
	ds_read_b128 v[202:205], v197 offset:57344
	v_add_f32_e32 v64, v159, v64
	v_add_f32_e32 v64, v144, v64
	v_add_f32_e32 v64, v145, v64
	v_add_f32_e32 v64, v146, v64
	v_add_u32_e32 v197, s4, v192
	v_add_f32_e32 v64, v147, v64
	s_waitcnt lgkmcnt(1)
	v_mfma_f32_32x32x16_bf16 v[96:111], v[198:201], v[120:123], v[96:111]
	ds_read_b128 v[198:201], v197 offset:49152
	ds_read_b128 v[206:209], v197 offset:57344
	v_add_f32_e32 v64, v148, v64
	v_exp_f32_e32 v222, v65
	v_add_f32_e32 v64, v149, v64
	v_exp_f32_e32 v223, v66
	v_add_f32_e32 v64, v150, v64
	v_exp_f32_e32 v224, v67
	s_waitcnt lgkmcnt(2)
	v_mfma_f32_32x32x16_bf16 v[80:95], v[202:205], v[120:123], v[80:95]
	v_add_f32_e32 v64, v151, v64
	v_add_f32_e32 v64, v221, v64
	v_add_f32_e32 v64, v222, v64
	v_add_f32_e32 v64, v223, v64
	v_exp_f32_e32 v71, v71
	v_add_f32_e32 v64, v224, v64
	v_add_u32_e32 v197, s4, v194
	s_waitcnt lgkmcnt(1)
	v_mfma_f32_32x32x16_bf16 v[96:111], v[198:201], v[116:119], v[96:111]
	v_exp_f32_e32 v199, v68
	v_exp_f32_e32 v200, v69
	v_exp_f32_e32 v201, v70
	v_exp_f32_e32 v225, v72
	v_add_f32_e32 v64, v199, v64
	ds_read_b128 v[202:205], v197 offset:49152
	ds_read_b128 v[210:213], v197 offset:57344
	v_exp_f32_e32 v226, v73
	s_waitcnt lgkmcnt(2)
	v_mfma_f32_32x32x16_bf16 v[80:95], v[206:209], v[116:119], v[80:95]
	v_add_f32_e32 v64, v200, v64
	v_exp_f32_e32 v227, v74
	v_add_f32_e32 v64, v201, v64
	v_exp_f32_e32 v206, v75
	v_add_f32_e32 v64, v71, v64
	v_exp_f32_e32 v207, v76
	v_add_f32_e32 v64, v225, v64
	v_exp_f32_e32 v208, v77
	v_add_f32_e32 v64, v226, v64
	v_exp_f32_e32 v209, v78
	s_waitcnt lgkmcnt(1)
	v_mfma_f32_32x32x16_bf16 v[96:111], v[202:205], v[112:115], v[96:111]
	v_add_f32_e32 v64, v227, v64
	v_exp_f32_e32 v79, v79
	v_add_f32_e32 v64, v206, v64
	v_add_f32_e32 v64, v207, v64
	v_add_f32_e32 v64, v208, v64
	v_add_f32_e32 v64, v209, v64
	v_add_f32_e32 v197, v79, v64
	s_waitcnt lgkmcnt(0)
	v_mfma_f32_32x32x16_bf16 v[80:95], v[210:213], v[112:115], v[80:95]
	v_cvt_pk_bf16_f32 v64, v152, v153
	v_cvt_pk_bf16_f32 v65, v154, v155
	v_cvt_pk_bf16_f32 v66, v156, v157
	v_cvt_pk_bf16_f32 v67, v158, v159
	v_cvt_pk_bf16_f32 v72, v144, v145
	v_cvt_pk_bf16_f32 v73, v146, v147
	v_cvt_pk_bf16_f32 v74, v148, v149
	v_cvt_pk_bf16_f32 v75, v150, v151
	v_cvt_pk_bf16_f32 v68, v221, v222
	v_cvt_pk_bf16_f32 v69, v223, v224
	v_cvt_pk_bf16_f32 v70, v199, v200
	v_cvt_pk_bf16_f32 v71, v201, v71
	v_cvt_pk_bf16_f32 v76, v225, v226
	v_cvt_pk_bf16_f32 v77, v227, v206
	v_cvt_pk_bf16_f32 v78, v207, v208
	v_cvt_pk_bf16_f32 v79, v209, v79
	global_load_dwordx4 v[144:147], v244, s[98:99]
	global_load_dwordx4 v[148:151], v245, s[98:99]
	global_load_dwordx4 v[152:155], v242, s[98:99]
	global_load_dwordx4 v[156:159], v243, s[98:99]
	s_add_u32 s98, s98, 0x10000
	s_addc_u32 s99, s99, 0
	v_lshl_add_u32 v199, s18, 14, v181
	ds_read_b64_tr_b16 v[200:201], v199 offset:0
	ds_read_b64_tr_b16 v[202:203], v199 offset:0x100
	ds_read_b64_tr_b16 v[204:205], v199 offset:0x1000
	ds_read_b64_tr_b16 v[206:207], v199 offset:0x1100
	ds_read_b64_tr_b16 v[208:209], v199 offset:0x2000
	ds_read_b64_tr_b16 v[210:211], v199 offset:0x2100
	ds_read_b64_tr_b16 v[222:223], v199 offset:0x3000
	ds_read_b64_tr_b16 v[224:225], v199 offset:0x3100
	s_waitcnt lgkmcnt(6)
	v_mfma_f32_32x32x16_bf16 v[0:15], v[64:67], v[200:203], v[0:15]
	v_max_f32_e32 v200, v96, v97
	v_max3_f32 v200, v200, v98, v99
	v_max3_f32 v200, v200, v100, v101
	v_max3_f32 v200, v200, v102, v103
	v_max3_f32 v200, v200, v104, v105
	s_waitcnt lgkmcnt(4)
	v_mfma_f32_32x32x16_bf16 v[0:15], v[72:75], v[204:207], v[0:15]
	v_max3_f32 v200, v200, v106, v107
	v_max3_f32 v202, v200, v108, v109
	ds_read_b64_tr_b16 v[200:201], v199 offset:0x200
	v_max3_f32 v212, v202, v110, v111
	ds_read_b64_tr_b16 v[202:203], v199 offset:0x300
	ds_read_b64_tr_b16 v[204:205], v199 offset:0x1200
	ds_read_b64_tr_b16 v[206:207], v199 offset:0x1300
	s_waitcnt lgkmcnt(6)
	v_mfma_f32_32x32x16_bf16 v[0:15], v[68:71], v[208:211], v[0:15]
	ds_read_b64_tr_b16 v[208:209], v199 offset:0x2200
	ds_read_b64_tr_b16 v[210:211], v199 offset:0x2300
	ds_read_b64_tr_b16 v[226:227], v199 offset:0x3200
	ds_read_b64_tr_b16 v[228:229], v199 offset:0x3300
	s_waitcnt lgkmcnt(8)
	v_mfma_f32_32x32x16_bf16 v[0:15], v[76:79], v[222:225], v[0:15]
	s_waitcnt lgkmcnt(6)
	v_mfma_f32_32x32x16_bf16 v[48:63], v[64:67], v[200:203], v[48:63]
	v_max3_f32 v212, v212, v80, v81
	v_max3_f32 v200, v212, v82, v83
	ds_read_b64_tr_b16 v[202:203], v199 offset:0x400
	v_max3_f32 v200, v200, v84, v85
	v_max3_f32 v200, v200, v86, v87
	v_max3_f32 v200, v200, v88, v89
	v_max3_f32 v200, v200, v90, v91
	s_waitcnt lgkmcnt(5)
	v_mfma_f32_32x32x16_bf16 v[48:63], v[72:75], v[204:207], v[48:63]
	ds_read_b64_tr_b16 v[204:205], v199 offset:0x500
	ds_read_b64_tr_b16 v[206:207], v199 offset:0x1400
	v_max3_f32 v200, v200, v92, v93
	v_max3_f32 v200, v200, v94, v95
	s_waitcnt lgkmcnt(5)
	v_mfma_f32_32x32x16_bf16 v[48:63], v[68:71], v[208:211], v[48:63]
	ds_read_b64_tr_b16 v[208:209], v199 offset:0x1500
	ds_read_b64_tr_b16 v[210:211], v199 offset:0x2400
	ds_read_b64_tr_b16 v[212:213], v199 offset:0x2500
	ds_read_b64_tr_b16 v[222:223], v199 offset:0x3400
	ds_read_b64_tr_b16 v[224:225], v199 offset:0x3500
	s_waitcnt lgkmcnt(8)
	v_mfma_f32_32x32x16_bf16 v[48:63], v[76:79], v[226:229], v[48:63]
	s_waitcnt lgkmcnt(6)
	v_mfma_f32_32x32x16_bf16 v[32:47], v[64:67], v[202:205], v[32:47]
	v_cmp_ge_f32_e32 vcc, s63, v200
	s_cmp_eq_u64 vcc, exec
	s_waitcnt lgkmcnt(4)
	v_mfma_f32_32x32x16_bf16 v[32:47], v[72:75], v[206:209], v[32:47]
	s_waitcnt lgkmcnt(2)
	v_mfma_f32_32x32x16_bf16 v[32:47], v[68:71], v[210:213], v[32:47]
	s_waitcnt lgkmcnt(0)
	v_mfma_f32_32x32x16_bf16 v[32:47], v[76:79], v[222:225], v[32:47]
	s_cbranch_scc0 .LBB0_438
	v_mov_b32_e32 v200, 1.0
	s_mov_b64 s[100:101], 0

.LBB0_440:
	s_setprio 0
	v_mov_b32_e32 v246, v180
	s_nop 1
	v_permlane32_swap_b32_e32 v180, v246
	v_add_f32_e32 v180, v180, v246
	v_or_b32_e32 v136, 0x2000, v190
	v_add_u32_e32 v90, s58, v185
	v_add3_u32 v96, v182, v136, s58
	ds_read_b128 v[128:131], v90
	ds_read_b128 v[132:135], v96
	v_xor_b32_e32 v80, 0x80000000, v195
	v_mov_b32_e32 v81, v80
	v_mov_b64_e32 v[82:83], v[80:81]
	v_mov_b64_e32 v[84:85], v[80:81]
	v_mov_b64_e32 v[86:87], v[80:81]
	v_mov_b64_e32 v[88:89], v[80:81]
	v_mov_b64_e32 v[90:91], v[80:81]
	v_mov_b64_e32 v[92:93], v[80:81]
	v_mov_b64_e32 v[94:95], v[80:81]
	v_exp_f32_e32 v137, v65
	v_exp_f32_e32 v138, v70
	s_waitcnt lgkmcnt(1)
	v_mfma_f32_32x32x16_bf16 v[96:111], v[128:131], v[124:127], v[80:95]
	v_add3_u32 v128, v187, v136, s58
	ds_read_b128 v[128:131], v128
	v_exp_f32_e32 v139, v71
	v_exp_f32_e32 v140, v72
	v_exp_f32_e32 v79, v79
	v_cvt_pk_bf16_f32 v65, v154, v155
	v_cvt_pk_bf16_f32 v70, v148, v149
	s_waitcnt lgkmcnt(1)
	v_mfma_f32_32x32x16_bf16 v[80:95], v[132:135], v[124:127], v[80:95]
	v_add_u32_e32 v124, s58, v189
	ds_read_b128 v[124:127], v124
	v_add3_u32 v132, v191, v136, s58
	v_cvt_pk_bf16_f32 v71, v150, v151
	s_waitcnt lgkmcnt(0)
	v_mfma_f32_32x32x16_bf16 v[96:111], v[124:127], v[120:123], v[96:111]
	v_add_u32_e32 v124, s58, v192
	ds_read_b128 v[124:127], v124
	v_mfma_f32_32x32x16_bf16 v[80:95], v[128:131], v[120:123], v[80:95]
	ds_read_b128 v[120:123], v132
	v_add3_u32 v132, v193, v136, s58
	v_exp_f32_e32 v136, v64
	v_add_f32_e32 v64, 0, v152
	v_add_f32_e32 v64, v153, v64
	v_add_f32_e32 v64, v154, v64
	v_add_f32_e32 v64, v155, v64
	v_add_f32_e32 v64, v156, v64
	v_add_f32_e32 v64, v157, v64
	v_add_f32_e32 v64, v158, v64
	v_add_f32_e32 v64, v159, v64
	v_add_f32_e32 v64, v144, v64
	v_add_f32_e32 v64, v145, v64
	v_add_f32_e32 v64, v146, v64
	v_add_f32_e32 v64, v147, v64
	v_add_f32_e32 v64, v148, v64
	v_add_f32_e32 v64, v149, v64
	s_waitcnt lgkmcnt(1)
	v_mfma_f32_32x32x16_bf16 v[96:111], v[124:127], v[116:119], v[96:111]
	v_exp_f32_e32 v124, v66
	v_add_f32_e32 v64, v150, v64
	v_exp_f32_e32 v125, v67
	v_add_f32_e32 v64, v151, v64
	v_exp_f32_e32 v126, v68
	v_add_f32_e32 v64, v136, v64
	v_exp_f32_e32 v127, v69
	v_add_f32_e32 v64, v137, v64
	s_waitcnt lgkmcnt(0)
	v_mfma_f32_32x32x16_bf16 v[80:95], v[120:123], v[116:119], v[80:95]
	v_add_f32_e32 v64, v124, v64
	v_add_f32_e32 v64, v125, v64
	v_add_u32_e32 v128, s58, v194
	v_add_f32_e32 v64, v126, v64
	ds_read_b128 v[128:131], v128
	ds_read_b128 v[132:135], v132
	v_exp_f32_e32 v116, v73
	v_add_f32_e32 v64, v127, v64
	v_exp_f32_e32 v117, v74
	v_add_f32_e32 v64, v138, v64
	v_exp_f32_e32 v118, v75
	v_add_f32_e32 v64, v139, v64
	v_exp_f32_e32 v119, v76
	v_add_f32_e32 v64, v140, v64
	v_exp_f32_e32 v120, v77
	v_add_f32_e32 v64, v116, v64
	v_exp_f32_e32 v121, v78
	s_waitcnt lgkmcnt(1)
	v_mfma_f32_32x32x16_bf16 v[96:111], v[128:131], v[112:115], v[96:111]
	v_add_f32_e32 v64, v117, v64
	v_add_f32_e32 v64, v118, v64
	v_add_f32_e32 v64, v119, v64
	v_add_f32_e32 v64, v120, v64
	v_add_f32_e32 v64, v121, v64
	v_cvt_pk_bf16_f32 v66, v156, v157
	v_cvt_pk_bf16_f32 v67, v158, v159
	s_waitcnt lgkmcnt(0)
	v_mfma_f32_32x32x16_bf16 v[80:95], v[132:135], v[112:115], v[80:95]
	v_add_f32_e32 v112, v79, v64
	v_mov_b32_e32 v113, v112
	v_cvt_pk_bf16_f32 v64, v152, v153
	v_cvt_pk_bf16_f32 v68, v144, v145
	v_cvt_pk_bf16_f32 v69, v146, v147
	v_cvt_pk_bf16_f32 v72, v136, v137
	v_cvt_pk_bf16_f32 v73, v124, v125
	v_cvt_pk_bf16_f32 v74, v126, v127
	v_cvt_pk_bf16_f32 v75, v138, v139
	v_cvt_pk_bf16_f32 v76, v140, v116
	v_cvt_pk_bf16_f32 v77, v117, v118
	v_cvt_pk_bf16_f32 v78, v119, v120
	v_cvt_pk_bf16_f32 v79, v121, v79
	v_permlane32_swap_b32_e32 v112, v113
	ds_read_b64_tr_b16 v[114:115], v181 offset:0
	ds_read_b64_tr_b16 v[116:117], v181 offset:0x100
	ds_read_b64_tr_b16 v[118:119], v181 offset:0x1000
	ds_read_b64_tr_b16 v[120:121], v181 offset:0x1100
	ds_read_b64_tr_b16 v[122:123], v181 offset:0x2000
	ds_read_b64_tr_b16 v[124:125], v181 offset:0x2100
	ds_read_b64_tr_b16 v[126:127], v181 offset:0x3000
	ds_read_b64_tr_b16 v[128:129], v181 offset:0x3100
	s_waitcnt lgkmcnt(0)
	s_nop 0
	v_mfma_f32_32x32x16_bf16 v[0:15], v[64:67], v[114:117], v[0:15]
	v_max_f32_e32 v114, v97, v97
	v_max_f32_e32 v115, v96, v96
	v_max_f32_e32 v114, v115, v114
	v_max3_f32 v114, v114, v98, v99
	v_max3_f32 v114, v114, v100, v101
	v_max3_f32 v114, v114, v102, v103
	v_max3_f32 v114, v114, v104, v105
	v_mfma_f32_32x32x16_bf16 v[0:15], v[68:71], v[118:121], v[0:15]
	v_max3_f32 v114, v114, v106, v107
	v_max3_f32 v116, v114, v108, v109
	ds_read_b64_tr_b16 v[114:115], v181 offset:0x200
	v_max3_f32 v134, v116, v110, v111
	ds_read_b64_tr_b16 v[116:117], v181 offset:0x300
	ds_read_b64_tr_b16 v[118:119], v181 offset:0x1200
	ds_read_b64_tr_b16 v[120:121], v181 offset:0x1300
	v_mfma_f32_32x32x16_bf16 v[0:15], v[72:75], v[122:125], v[0:15]
	ds_read_b64_tr_b16 v[122:123], v181 offset:0x2200
	ds_read_b64_tr_b16 v[124:125], v181 offset:0x2300
	ds_read_b64_tr_b16 v[130:131], v181 offset:0x3200
	ds_read_b64_tr_b16 v[132:133], v181 offset:0x3300
	s_waitcnt lgkmcnt(0)
	v_mfma_f32_32x32x16_bf16 v[0:15], v[76:79], v[126:129], v[0:15]
	v_mfma_f32_32x32x16_bf16 v[48:63], v[64:67], v[114:117], v[48:63]
	v_max3_f32 v126, v134, v80, v81
	v_max3_f32 v114, v126, v82, v83
	ds_read_b64_tr_b16 v[116:117], v181 offset:0x400
	v_max3_f32 v114, v114, v84, v85
	v_max3_f32 v114, v114, v86, v87
	v_max3_f32 v114, v114, v88, v89
	v_max3_f32 v114, v114, v90, v91
	v_mfma_f32_32x32x16_bf16 v[48:63], v[68:71], v[118:121], v[48:63]
	ds_read_b64_tr_b16 v[118:119], v181 offset:0x500
	ds_read_b64_tr_b16 v[120:121], v181 offset:0x1400
	v_max3_f32 v114, v114, v92, v93
	v_max3_f32 v114, v114, v94, v95
	v_mov_b32_e32 v115, v114
	s_nop 1
	v_permlane32_swap_b32_e32 v114, v115
	v_mfma_f32_32x32x16_bf16 v[48:63], v[72:75], v[122:125], v[48:63]
	ds_read_b64_tr_b16 v[122:123], v181 offset:0x1500
	ds_read_b64_tr_b16 v[124:125], v181 offset:0x2400
	ds_read_b64_tr_b16 v[126:127], v181 offset:0x2500
	ds_read_b64_tr_b16 v[134:135], v181 offset:0x3400
	ds_read_b64_tr_b16 v[136:137], v181 offset:0x3500
	s_waitcnt lgkmcnt(0)
	v_max_f32_e32 v115, v115, v115
	v_mfma_f32_32x32x16_bf16 v[48:63], v[76:79], v[130:133], v[48:63]
	v_max_f32_e32 v114, v114, v114
	v_max_f32_e32 v115, v114, v115
	v_mfma_f32_32x32x16_bf16 v[32:47], v[64:67], v[116:119], v[32:47]
	v_cmp_ge_f32_e32 vcc, s63, v115
	s_cmp_eq_u64 vcc, exec
	v_mov_b32_e32 v114, 1.0
	v_mfma_f32_32x32x16_bf16 v[32:47], v[68:71], v[120:123], v[32:47]
	v_mfma_f32_32x32x16_bf16 v[32:47], v[72:75], v[124:127], v[32:47]
	v_mfma_f32_32x32x16_bf16 v[32:47], v[76:79], v[134:137], v[32:47]
	s_cbranch_scc0 .LBB0_451

.LBB0_805:
	s_lshl_b32 s0, s39, 10
	s_and_b32 s6, s0, 0x800000
	s_lshl_b32 s0, s43, 1
	s_and_b32 s65, s0, 0x300
	s_lshl_b32 s0, s2, 11
	s_lshl_b32 s1, s2, 4
	s_and_b32 s0, s0, 0x2000
	s_and_b32 s1, s1, 0xffffff80
	s_add_i32 s1, s0, s1
	v_or_b32_e32 v171, s1, v170
	v_or_b32_e32 v0, v171, v169
	v_ashrrev_i32_e32 v1, 31, v0
	s_lshl_b32 s1, s2, 7
	v_lshlrev_b64 v[0:1], 10, v[0:1]
	s_and_b32 s64, s1, 0x180
	v_lshl_add_u64 v[0:1], s[86:87], 0, v[0:1]
	s_lshl_b32 s4, s64, 1
	s_mov_b32 s5, s7
	v_lshl_add_u64 v[0:1], v[0:1], 0, s[4:5]
	s_lshl_b32 s5, s0, 10
	s_add_u32 s0, s33, s5
	s_addc_u32 s1, s34, 0
	s_add_u32 s0, s0, s4
	v_mov_b32_e32 v174, v168
	v_lshl_add_u64 v[0:1], v[160:161], 1, v[0:1]
	s_addc_u32 s1, s1, 0
	v_lshl_add_u64 v[0:1], v[0:1], 0, v[162:163]
	v_ashrrev_i32_e32 v16, 4, v174
	s_add_u32 s5, s35, s5
	v_lshlrev_b32_e32 v20, 3, v174
	v_add_u32_e32 v18, 32, v16
	s_addc_u32 s16, s38, 0
	global_load_dwordx4 v[124:127], v[0:1], off
	global_load_dwordx4 v[120:123], v[0:1], off offset:32
	global_load_dwordx4 v[116:119], v[0:1], off offset:64
	global_load_dwordx4 v[112:115], v[0:1], off offset:96
	v_and_b32_e32 v0, 0x78, v20
	v_ashrrev_i32_e32 v17, 31, v16
	v_ashrrev_i32_e32 v19, 31, v18
	s_add_u32 s4, s5, s4
	v_lshlrev_b32_e32 v21, 1, v0
	v_lshlrev_b64 v[48:49], 10, v[16:17]
	v_lshlrev_b64 v[12:13], 10, v[18:19]
	s_addc_u32 s5, s16, 0
	v_or_b32_e32 v50, v48, v21
	v_mov_b32_e32 v51, v49
	v_or_b32_e32 v12, v12, v21
	v_lshl_add_u64 v[0:1], s[4:5], 0, v[50:51]
	v_lshl_add_u64 v[4:5], s[4:5], 0, v[12:13]
	s_barrier
	global_load_dwordx4 v[0:3], v[0:1], off
	s_nop 0
	global_load_dwordx4 v[4:7], v[4:5], off
	v_lshl_add_u64 v[8:9], s[0:1], 0, v[50:51]
	global_load_dwordx4 v[8:11], v[8:9], off
	v_lshl_add_u64 v[12:13], s[0:1], 0, v[12:13]
	global_load_dwordx4 v[12:15], v[12:13], off
	v_and_b32_e32 v22, 0xfffff0, v16
	v_lshlrev_b32_e32 v23, 1, v16
	v_lshrrev_b32_e32 v24, 1, v16
	v_and_b32_e32 v25, 3, v16
	v_and_or_b32 v22, v23, 8, v22
	v_and_or_b32 v23, v24, 4, v25
	v_and_b32_e32 v24, 0xfffff0, v18
	v_lshlrev_b32_e32 v25, 1, v18
	v_and_b32_e32 v17, 0x70, v174
	v_bfe_u32 v20, v20, 5, 2
	v_lshlrev_b32_e32 v16, 8, v16
	v_lshrrev_b32_e32 v22, 1, v22
	v_and_or_b32 v24, v25, 8, v24
	v_bitop3_b32 v183, v21, v16, v17 bitop3:0xde
	v_or_b32_e32 v16, v22, v20
	v_lshrrev_b32_e32 v22, 1, v24
	v_lshlrev_b32_e32 v23, 6, v23
	v_and_b32_e32 v26, 48, v21
	v_lshlrev_b32_e32 v16, 9, v16
	v_or_b32_e32 v20, v22, v20
	v_or3_b32 v184, v16, v23, v26
	v_lshlrev_b32_e32 v16, 9, v20
	v_bfe_u32 v172, v174, 5, 1
	v_ashrrev_i32_e32 v175, 8, v174
	v_lshlrev_b32_e32 v52, 4, v174
	v_or3_b32 v186, v16, v23, v26
	v_add_u32_e32 v84, 16, v184
	v_and_b32_e32 v173, 31, v174
	v_lshlrev_b32_e32 v19, 7, v175
	v_add_u32_e32 v24, 16, v183
	v_add_u32_e32 v85, 16, v186
	s_waitcnt vmcnt(0)
	v_lshlrev_b32_e32 v176, 4, v172
	v_lshlrev_b32_e32 v190, 8, v173
	v_and_b32_e32 v86, 63, v174
	v_lshl_add_u64 v[60:61], v[50:51], 0, s[14:15]
	v_lshl_add_u64 v[64:65], v[50:51], 0, s[36:37]
	v_lshl_add_u64 v[56:57], s[4:5], 0, v[64:65]
	v_lshl_add_u64 v[64:65], s[0:1], 0, v[64:65]
	s_cmp_lg_u32 16, -1
	s_cselect_b32 s16, 16, 0
	s_mov_b32 s17, s7
	s_mov_b32 s18, s7
	s_mov_b32 s19, s7
	s_mov_b32 s20, s7
	s_waitcnt vmcnt(3)
	ds_write_b128 v84, v[0:3]
	s_waitcnt vmcnt(2)
	ds_write_b128 v85, v[4:7]
	s_waitcnt vmcnt(1)
	ds_write_b128 v24, v[8:11] offset:49152
	v_and_b32_e32 v8, 0x70, v52
	v_lshlrev_b32_e32 v0, 8, v18
	v_bitop3_b32 v182, v176, v8, v19 bitop3:0x36
	v_bitop3_b32 v188, v21, v0, v17 bitop3:0xde
	v_add_u32_e32 v185, v182, v190
	v_add_u32_e32 v0, 16, v188
	v_add_u32_e32 v4, 16, v185
	s_waitcnt vmcnt(0)
	ds_write_b128 v0, v[12:15] offset:49152
	s_waitcnt lgkmcnt(0)
	s_barrier
	ds_read_b128 v[0:3], v4 offset:49152
	ds_read_b128 v[4:7], v4 offset:57344
	v_or_b32_e32 v9, v176, v19
	v_bitop3_b32 v187, v9, v8, 32 bitop3:0x36
	v_add_u32_e32 v189, v187, v190
	s_waitcnt lgkmcnt(0)
	v_mfma_f32_32x32x16_bf16 v[16:31], v[4:7], v[124:127], 0
	v_add_u32_e32 v4, 16, v189
	v_bitop3_b32 v193, v9, v8, s3 bitop3:0x36
	v_bitop3_b32 v191, v9, v8, 64 bitop3:0x36
	v_add_u32_e32 v194, v193, v190
	v_add_u32_e32 v192, v191, v190
	v_add_u32_e32 v8, 16, v194
	v_and_b32_e32 v5, 0x3fffffc0, v174
	v_mfma_f32_32x32x16_bf16 v[32:47], v[0:3], v[124:127], 0
	ds_read_b128 v[0:3], v4 offset:49152
	v_and_b32_e32 v11, 0xc0, v52
	v_add_u32_e32 v13, 16, v192
	ds_read_b128 v[52:55], v8 offset:57344
	v_lshl_add_u32 v177, v5, 2, s50
	ds_read_b128 v[4:7], v4 offset:57344
	v_lshlrev_b32_e32 v10, 3, v86
	s_waitcnt lgkmcnt(2)
	v_mfma_f32_32x32x16_bf16 v[32:47], v[0:3], v[120:123], v[32:47]
	v_lshlrev_b32_e32 v0, 1, v174
	v_and_b32_e32 v12, 32, v0
	ds_read_b128 v[0:3], v13 offset:49152
	v_and_or_b32 v11, v10, 24, v11
	s_mov_b32 s21, s7
	s_mov_b32 s22, s7
	s_mov_b32 s23, s7
	s_waitcnt lgkmcnt(0)
	v_mfma_f32_32x32x16_bf16 v[32:47], v[0:3], v[116:119], v[32:47]
	ds_read_b128 v[0:3], v8 offset:49152
	s_mov_b32 s24, s7
	s_mov_b32 s25, s7
	s_mov_b32 s26, s7
	s_mov_b32 s27, s7
	s_mov_b32 s28, s7
	s_mov_b32 s29, s7
	v_mfma_f32_32x32x16_bf16 v[16:31], v[4:7], v[120:123], v[16:31]
	v_and_b32_e32 v4, 0x100, v10
	v_lshlrev_b32_e32 v4, 3, v4
	v_or3_b32 v178, v11, v12, v4
	ds_read_b128 v[4:7], v13 offset:57344
	v_add_u32_e32 v181, s16, v178
	s_mov_b32 s16, s7
	s_mov_b32 s30, s7
	s_mov_b32 s31, s7
	s_waitcnt lgkmcnt(0)
	v_mfma_f32_32x32x16_bf16 v[16:31], v[4:7], v[116:119], v[16:31]
	v_lshl_add_u32 v179, v173, 2, v177
	v_mov_b32_e32 v196, 1.0
	v_mov_b32_e32 v180, 0
	v_mfma_f32_32x32x16_bf16 v[32:47], v[0:3], v[112:115], v[32:47]
	v_mov_b64_e32 v[0:1], s[16:17]
	v_mov_b64_e32 v[14:15], s[30:31]
	v_mov_b64_e32 v[2:3], s[18:19]
	v_mov_b64_e32 v[4:5], s[20:21]
	v_mov_b64_e32 v[6:7], s[22:23]
	v_mov_b64_e32 v[8:9], s[24:25]
	v_mov_b64_e32 v[10:11], s[26:27]
	v_mfma_f32_32x32x16_bf16 v[16:31], v[52:55], v[112:115], v[16:31]
	s_nop 3
	v_max_f32_e32 v52, v33, v33
	v_max_f32_e32 v53, v32, v32
	v_max_f32_e32 v52, v53, v52
	v_max3_f32 v52, v52, v34, v35
	v_max3_f32 v52, v52, v36, v37
	v_max3_f32 v52, v52, v38, v39
	v_max3_f32 v52, v52, v40, v41
	v_max3_f32 v52, v52, v42, v43
	v_max3_f32 v52, v52, v44, v45
	v_max3_f32 v66, v52, v46, v47
	v_lshl_add_u64 v[52:53], s[4:5], 0, v[60:61]
	v_lshl_add_u64 v[60:61], s[0:1], 0, v[60:61]
	global_load_dwordx4 v[52:55], v[52:53], off
	s_nop 0
	global_load_dwordx4 v[56:59], v[56:57], off
	v_mov_b64_e32 v[12:13], s[28:29]
	global_load_dwordx4 v[60:63], v[60:61], off
	s_mov_b32 s19, 1
	global_load_dwordx4 v[80:83], v[64:65], off
	v_max3_f32 v64, v66, v16, v17
	v_max3_f32 v64, v64, v18, v19
	v_max3_f32 v64, v64, v20, v21
	v_max3_f32 v64, v64, v22, v23
	v_max3_f32 v64, v64, v24, v25
	v_max3_f32 v64, v64, v26, v27
	v_max3_f32 v64, v64, v28, v29
	v_max3_f32 v70, v64, v30, v31
	v_lshl_add_u64 v[64:65], v[50:51], 0, s[40:41]
	v_lshl_add_u64 v[66:67], s[0:1], 0, v[64:65]
	v_lshl_add_u64 v[50:51], v[50:51], 0, s[44:45]
	v_lshl_add_u64 v[64:65], s[4:5], 0, v[64:65]
	v_lshl_add_u64 v[68:69], s[0:1], 0, v[50:51]
	global_load_dwordx4 v[136:139], v[66:67], off
	global_load_dwordx4 v[128:131], v[68:69], off
	v_lshl_add_u64 v[50:51], s[4:5], 0, v[50:51]
	global_load_dwordx4 v[140:143], v[64:65], off
	global_load_dwordx4 v[132:135], v[50:51], off
	v_mov_b32_e32 v71, v70
	s_nop 1
	v_permlane32_swap_b32_e32 v70, v71
	v_max_f32_e32 v50, v71, v71
	v_max_f32_e32 v51, v70, v70
	v_max_f32_e32 v50, v51, v50
	v_sub_f32_e32 v64, v16, v50
	v_add_u32_e32 v16, s58, v183
	v_sub_f32_e32 v32, v32, v50
	v_sub_f32_e32 v33, v33, v50
	v_sub_f32_e32 v34, v34, v50
	v_sub_f32_e32 v35, v35, v50
	v_sub_f32_e32 v36, v36, v50
	v_sub_f32_e32 v37, v37, v50
	v_sub_f32_e32 v38, v38, v50
	v_sub_f32_e32 v39, v39, v50
	v_sub_f32_e32 v40, v40, v50
	v_sub_f32_e32 v41, v41, v50
	v_sub_f32_e32 v42, v42, v50
	v_sub_f32_e32 v43, v43, v50
	v_sub_f32_e32 v44, v44, v50
	v_sub_f32_e32 v45, v45, v50
	v_sub_f32_e32 v46, v46, v50
	v_sub_f32_e32 v47, v47, v50
	v_sub_f32_e32 v66, v18, v50
	s_waitcnt vmcnt(4)
	s_waitcnt vmcnt(7)
	ds_write_b128 v84, v[52:55] offset:16384
	s_waitcnt vmcnt(6)
	ds_write_b128 v85, v[56:59] offset:16384
	v_and_b32_e32 v18, 15, v174
	s_waitcnt vmcnt(5)
	ds_write_b128 v16, v[60:63]
	v_add_u32_e32 v16, s58, v188
	v_sub_f32_e32 v65, v17, v50
	v_exp_f32_e32 v152, v32
	v_exp_f32_e32 v153, v33
	v_exp_f32_e32 v154, v34
	v_exp_f32_e32 v155, v35
	v_exp_f32_e32 v156, v36
	v_exp_f32_e32 v157, v37
	v_exp_f32_e32 v158, v38
	v_exp_f32_e32 v159, v39
	v_exp_f32_e32 v144, v40
	v_exp_f32_e32 v145, v41
	v_exp_f32_e32 v146, v42
	v_exp_f32_e32 v147, v43
	v_exp_f32_e32 v148, v44
	v_exp_f32_e32 v149, v45
	v_exp_f32_e32 v150, v46
	v_exp_f32_e32 v151, v47
	s_waitcnt vmcnt(4)
	ds_write_b128 v16, v[80:83]
	v_lshl_add_u64 v[16:17], s[6:7], 0, v[48:49]
	v_lshlrev_b32_e32 v18, 4, v18
	v_or3_b32 v16, v16, s65, v18
	v_add_f32_e32 v195, 0, v50
	v_sub_f32_e32 v79, v31, v50
	v_sub_f32_e32 v78, v30, v50
	v_sub_f32_e32 v77, v29, v50
	v_sub_f32_e32 v76, v28, v50
	v_sub_f32_e32 v75, v27, v50
	v_sub_f32_e32 v74, v26, v50
	v_sub_f32_e32 v73, v25, v50
	v_sub_f32_e32 v72, v24, v50
	v_sub_f32_e32 v71, v23, v50
	v_sub_f32_e32 v70, v22, v50
	v_sub_f32_e32 v69, v21, v50
	v_sub_f32_e32 v68, v20, v50
	v_sub_f32_e32 v67, v19, v50
	v_lshl_add_u64 v[166:167], s[12:13], 0, v[16:17]
	v_mov_b64_e32 v[62:63], v[14:15]
	v_mov_b64_e32 v[46:47], v[14:15]
	v_mov_b64_e32 v[30:31], v[14:15]
	v_cmp_gt_u32_e64 s[0:1], 32, v86
	v_mov_b64_e32 v[60:61], v[12:13]
	v_mov_b64_e32 v[58:59], v[10:11]
	v_mov_b64_e32 v[56:57], v[8:9]
	v_mov_b64_e32 v[54:55], v[6:7]
	v_mov_b64_e32 v[52:53], v[4:5]
	v_mov_b64_e32 v[50:51], v[2:3]
	v_mov_b64_e32 v[48:49], v[0:1]
	v_mov_b64_e32 v[44:45], v[12:13]
	v_mov_b64_e32 v[42:43], v[10:11]
	v_mov_b64_e32 v[40:41], v[8:9]
	v_mov_b64_e32 v[38:39], v[6:7]
	v_mov_b64_e32 v[36:37], v[4:5]
	v_mov_b64_e32 v[34:35], v[2:3]
	v_mov_b64_e32 v[32:33], v[0:1]
	v_mov_b64_e32 v[28:29], v[12:13]
	v_mov_b64_e32 v[26:27], v[10:11]
	v_mov_b64_e32 v[24:25], v[8:9]
	v_mov_b64_e32 v[22:23], v[6:7]
	v_mov_b64_e32 v[20:21], v[4:5]
	v_mov_b64_e32 v[18:19], v[2:3]
	v_mov_b64_e32 v[16:17], v[0:1]
	s_mov_b32 s6, 1
	s_mov_b32 s18, 0
	s_waitcnt lgkmcnt(0)
	s_barrier
	v_add_co_u32_e32 v242, vcc, s61, v166
	s_nop 1
	v_addc_co_u32_e32 v243, vcc, -1, v167, vcc
	s_nop 0
	v_readfirstlane_b32 s98, v242
	v_readfirstlane_b32 s99, v243
	s_nop 1
	v_subrev_u32_e32 v242, s98, v242
	v_add_u32_e32 v243, 0x8000, v242
	v_add_u32_e32 v244, 0x1000000, v242
	v_add_u32_e32 v245, 0x1008000, v242
	v_cmp_lt_u32_e32 vcc, 0xff, v214
	s_nop 4
	s_cbranch_vccz .Lprio_a1
	s_setprio 1
